# v9 + attention: gains loads issued before the Q/K wait (one combined wait); rsqrt denormal-rescale sequence removed (x>=1e-6 always, exact)
# baseline (speedup 1.0000x reference)
; #define LAS __attribute__((address_space(3)))
; __device__ __forceinline__ float shx(float v, int lane, int mask) { return __int_as_float(__builtin_amdgcn_ds_bpermute((lane ^ mask) << 2, __float_as_int(v))); }
; __device__ __forceinline__ unsigned cvt_pk_bf16(float lo, float hi) { unsigned r; asm volatile("v_cvt_pk_bf16_f32 %0, %1, %2" : "=v"(r) : "v"(lo), "v"(hi)); return r; }
; __device__ __forceinline__ float bflo(unsigned u) { return __uint_as_float(u << 16); }
; __device__ __forceinline__ float bfhi(unsigned u) { return __uint_as_float(u & 0xffff0000u); }
; __device__ __forceinline__ void attn_stream(const int wv, LAS unsigned char* lds, unsigned ldsb, const float* __restrict__ qng, const float* __restrict__ kng, const bf16_t* __restrict__ qkvr, bf16_t* __restrict__ og, float* __restrict__ lse, ...
;     ...
;             float gq[8], gk[8];
;             int c8 = c16 * 8; asm volatile("" : "+v"(c8));
; #pragma unroll
;             for (int j = 0; j < 8; ++j) { gq[j] = qng[hh * 128 + c8 + j] * 0.08838834764831845f; gk[j] = kng[hh * 128 + c8 + j]; }
; #pragma unroll
;             for (int it = 0; it < 12; ++it) {
;                 const u32x4 v = it < 4 ? qr[it] : kr[it - 4];
;                 float f[8] = {bflo(v.x), bfhi(v.x), bflo(v.y), bfhi(v.y), bflo(v.z), bfhi(v.z), bflo(v.w), bfhi(v.w)};
;                 float ss = 0.f;
; #pragma unroll
;                 for (int j = 0; j < 8; ++j) ss += f[j] * f[j];
;                 ss += shx(ss, lane, 1); ss += shx(ss, lane, 2); ss += shx(ss, lane, 4); ss += shx(ss, lane, 8);
;                 const float rs = rsqrtf(ss * (1.0f / 128.0f) + EPS);
; #pragma unroll
;                 for (int j = 0; j < 8; ++j) f[j] *= rs * (it < 4 ? gq[j] : gk[j]);
;                 u32x4 o; o.x = cvt_pk_bf16(f[0], f[1]); o.y = cvt_pk_bf16(f[2], f[3]); o.z = cvt_pk_bf16(f[4], f[5]); o.w = cvt_pk_bf16(f[6], f[7]);
;                 if (it < 4) *(LAS u32x4*)(lds + QI + (rr + 32 * it) * PA + c16 * 16) = o;
;                 else *(LAS u32x4*)(lds + KI + (rr + 32 * (it - 4)) * PA + c16 * 16) = o;
.LBB0_329:
	s_ashr_i32 s94, s82, 6
	s_and_b32 s19, s82, 63
	s_and_b32 s10, s82, 0xffffff00
	s_cmpk_eq_i32 s10, 0x100
	s_cselect_b64 s[96:97], -1, 0
	s_and_b64 s[10:11], s[96:97], exec
	s_cselect_b32 s18, 2, 4
	s_cmpk_lt_u32 s82, 0x100
	s_cselect_b64 s[10:11], -1, 0
	s_and_b64 s[12:13], s[10:11], exec
	s_cselect_b32 s18, 0, s18
	v_mov_b32_e32 v1, v104
	s_lshl_b32 s92, s94, 7
	v_add_u32_e32 v2, s92, v1
	v_ashrrev_i32_e32 v3, 31, v2
	v_lshlrev_b64 v[2:3], 2, v[2:3]
	s_waitcnt lgkmcnt(0)
	v_lshl_add_u64 v[52:53], s[84:85], 0, v[2:3]
	global_load_dwordx4 v[60:63], v[52:53], off offset:16
	global_load_dwordx4 v[70:73], v[52:53], off
	v_lshl_add_u64 v[2:3], s[86:87], 0, v[2:3]
	global_load_dwordx4 v[52:55], v[2:3], off offset:16
	global_load_dwordx4 v[56:59], v[2:3], off
	s_waitcnt vmcnt(0)
	v_and_b32_e32 v74, 0xffff0000, v4
	v_and_b32_e32 v2, 0xffff0000, v5
	v_lshlrev_b32_e32 v3, 16, v5
	s_lshr_b32 s12, 64, s18
	s_add_i32 s12, s12, -1
	s_and_b32 s95, s12, s19
	s_lshl_b32 s20, s95, 7
	s_xor_b32 s13, s18, 6
	s_lshr_b32 s19, s19, s13
	s_ashr_i32 s93, s92, 31
	s_waitcnt vmcnt(3)
	v_mul_f32_e32 v64, 0x3db504f3, v62
	s_waitcnt vmcnt(2)
	v_mul_f32_e32 v67, 0x3db504f3, v70
	v_mul_f32_e32 v70, 0x3db504f3, v71
	v_lshlrev_b32_e32 v71, 16, v4
	v_mul_f32_e32 v62, v74, v74
	v_mul_f32_e32 v66, 0x3db504f3, v60
	v_mul_f32_e32 v65, 0x3db504f3, v61
	v_fmac_f32_e32 v62, v71, v71
	v_pk_mul_f32 v[60:61], v[2:3], v[2:3]
	v_mul_f32_e32 v69, 0x3db504f3, v72
	v_add_f32_e32 v61, v61, v62
	v_add_f32_e32 v72, v60, v61
	v_and_b32_e32 v60, 0xffff0000, v6
	v_lshlrev_b32_e32 v61, 16, v6
	v_mul_f32_e32 v1, 0x3db504f3, v63
	v_pk_mul_f32 v[62:63], v[60:61], v[60:61]
	v_mul_f32_e32 v68, 0x3db504f3, v73
	v_add_f32_e32 v63, v63, v72
	v_add_f32_e32 v75, v62, v63
	v_and_b32_e32 v62, 0xffff0000, v7
	v_lshlrev_b32_e32 v63, 16, v7
	v_pk_mul_f32 v[72:73], v[62:63], v[62:63]
	s_nop 0
	v_add_f32_e32 v73, v73, v75
	v_add_f32_e32 v72, v72, v73
	s_nop 1
	v_add_f32_dpp v72, v72, v72 quad_perm:[1,0,3,2] row_mask:0xf bank_mask:0xf
	s_nop 1
	v_add_f32_dpp v72, v72, v72 quad_perm:[2,3,0,1] row_mask:0xf bank_mask:0xf
	s_nop 1
	v_add_f32_dpp v72, v72, v72 row_half_mirror row_mask:0xf bank_mask:0xf
	s_nop 1
	v_add_f32_dpp v72, v72, v72 row_mirror row_mask:0xf bank_mask:0xf
	v_fmamk_f32 v72, v72, 0x3c000000, v185
	v_rsq_f32_e32 v72, v72
	s_nop 0
	v_mul_f32_e32 v73, v67, v72
	v_mul_f32_e32 v71, v73, v71
	v_mul_f32_e32 v73, v70, v72
	v_mul_f32_e32 v73, v73, v74
	v_mul_f32_e32 v74, v69, v72
	v_mul_f32_e32 v3, v74, v3
	v_mul_f32_e32 v74, v68, v72
	v_mul_f32_e32 v2, v74, v2
	v_mul_f32_e32 v74, v66, v72
	v_mul_f32_e32 v74, v74, v61
	v_mul_f32_e32 v61, v65, v72
	v_mul_f32_e32 v75, v61, v60
	v_mul_f32_e32 v60, v64, v72
	v_mul_f32_e32 v63, v60, v63
	v_mul_f32_e32 v60, v1, v72
	v_mul_f32_e32 v72, v60, v62
	v_cvt_pk_bf16_f32 v60, v71, v73
	v_cvt_pk_bf16_f32 v61, v3, v2
	v_cvt_pk_bf16_f32 v62, v74, v75
	v_and_b32_e32 v74, 0xffff0000, v8
	v_cvt_pk_bf16_f32 v63, v63, v72
	ds_write_b128 v108, v[60:63]
	v_lshlrev_b32_e32 v71, 16, v8
	v_mul_f32_e32 v62, v74, v74
	v_and_b32_e32 v2, 0xffff0000, v9
	v_lshlrev_b32_e32 v3, 16, v9
	v_fmac_f32_e32 v62, v71, v71
	v_pk_mul_f32 v[60:61], v[2:3], v[2:3]
	s_nop 0
	v_add_f32_e32 v61, v61, v62
	v_add_f32_e32 v72, v60, v61
	v_and_b32_e32 v60, 0xffff0000, v10
	v_lshlrev_b32_e32 v61, 16, v10
	v_pk_mul_f32 v[62:63], v[60:61], v[60:61]
	s_nop 0
	v_add_f32_e32 v63, v63, v72
	v_add_f32_e32 v75, v62, v63
	v_and_b32_e32 v62, 0xffff0000, v11
	v_lshlrev_b32_e32 v63, 16, v11
	v_pk_mul_f32 v[72:73], v[62:63], v[62:63]
	s_nop 0
	v_add_f32_e32 v73, v73, v75
	v_add_f32_e32 v72, v72, v73
	s_nop 1
	v_add_f32_dpp v72, v72, v72 quad_perm:[1,0,3,2] row_mask:0xf bank_mask:0xf
	s_nop 1
	v_add_f32_dpp v72, v72, v72 quad_perm:[2,3,0,1] row_mask:0xf bank_mask:0xf
	s_nop 1
	v_add_f32_dpp v72, v72, v72 row_half_mirror row_mask:0xf bank_mask:0xf
	s_nop 1
	v_add_f32_dpp v72, v72, v72 row_mirror row_mask:0xf bank_mask:0xf
	v_fmamk_f32 v72, v72, 0x3c000000, v185
	v_rsq_f32_e32 v72, v72
	s_nop 0
	v_mul_f32_e32 v73, v67, v72
	v_mul_f32_e32 v71, v73, v71
	v_mul_f32_e32 v73, v70, v72
	v_mul_f32_e32 v73, v73, v74
	v_mul_f32_e32 v74, v69, v72
	v_mul_f32_e32 v3, v74, v3
	v_mul_f32_e32 v74, v68, v72
	v_mul_f32_e32 v2, v74, v2
	v_mul_f32_e32 v74, v66, v72
	v_mul_f32_e32 v74, v74, v61
	v_mul_f32_e32 v61, v65, v72
	v_mul_f32_e32 v75, v61, v60
	v_mul_f32_e32 v60, v64, v72
	v_mul_f32_e32 v63, v60, v63
	v_mul_f32_e32 v60, v1, v72
	v_mul_f32_e32 v72, v60, v62
	v_cvt_pk_bf16_f32 v60, v71, v73
	v_cvt_pk_bf16_f32 v61, v3, v2
	v_cvt_pk_bf16_f32 v62, v74, v75
	v_and_b32_e32 v74, 0xffff0000, v12
	v_cvt_pk_bf16_f32 v63, v63, v72
	ds_write_b128 v108, v[60:63] offset:8704
	v_lshlrev_b32_e32 v71, 16, v12
	v_mul_f32_e32 v62, v74, v74
	v_and_b32_e32 v2, 0xffff0000, v13
	v_lshlrev_b32_e32 v3, 16, v13
	v_fmac_f32_e32 v62, v71, v71
	v_pk_mul_f32 v[60:61], v[2:3], v[2:3]
	s_nop 0
	v_add_f32_e32 v61, v61, v62
	v_add_f32_e32 v72, v60, v61
	v_and_b32_e32 v60, 0xffff0000, v14
	v_lshlrev_b32_e32 v61, 16, v14
	v_pk_mul_f32 v[62:63], v[60:61], v[60:61]
	s_nop 0
	v_add_f32_e32 v63, v63, v72
	v_add_f32_e32 v75, v62, v63
	v_and_b32_e32 v62, 0xffff0000, v15
	v_lshlrev_b32_e32 v63, 16, v15
	v_pk_mul_f32 v[72:73], v[62:63], v[62:63]
	s_nop 0
	v_add_f32_e32 v73, v73, v75
	v_add_f32_e32 v72, v72, v73
	s_nop 1
	v_add_f32_dpp v72, v72, v72 quad_perm:[1,0,3,2] row_mask:0xf bank_mask:0xf
	s_nop 1
	v_add_f32_dpp v72, v72, v72 quad_perm:[2,3,0,1] row_mask:0xf bank_mask:0xf
	s_nop 1
	v_add_f32_dpp v72, v72, v72 row_half_mirror row_mask:0xf bank_mask:0xf
	s_nop 1
	v_add_f32_dpp v72, v72, v72 row_mirror row_mask:0xf bank_mask:0xf
	v_fmamk_f32 v72, v72, 0x3c000000, v185
; #define LAS __attribute__((address_space(3)))
; __device__ __forceinline__ float shx(float v, int lane, int mask) { return __int_as_float(__builtin_amdgcn_ds_bpermute((lane ^ mask) << 2, __float_as_int(v))); }
; __device__ __forceinline__ unsigned cvt_pk_bf16(float lo, float hi) { unsigned r; asm volatile("v_cvt_pk_bf16_f32 %0, %1, %2" : "=v"(r) : "v"(lo), "v"(hi)); return r; }
; __device__ __forceinline__ float bflo(unsigned u) { return __uint_as_float(u << 16); }
; __device__ __forceinline__ float bfhi(unsigned u) { return __uint_as_float(u & 0xffff0000u); }
; __device__ __forceinline__ void attn_stream(const int wv, LAS unsigned char* lds, unsigned ldsb, const float* __restrict__ qng, const float* __restrict__ kng, const bf16_t* __restrict__ qkvr, bf16_t* __restrict__ og, float* __restrict__ lse, ...
;     ...
;             for (int j = 0; j < 8; ++j) { gq[j] = qng[hh * 128 + c8 + j] * 0.08838834764831845f; gk[j] = kng[hh * 128 + c8 + j]; }
; #pragma unroll
;             for (int it = 0; it < 12; ++it) {
;                 const u32x4 v = it < 4 ? qr[it] : kr[it - 4];
;                 float f[8] = {bflo(v.x), bfhi(v.x), bflo(v.y), bfhi(v.y), bflo(v.z), bfhi(v.z), bflo(v.w), bfhi(v.w)};
;                 float ss = 0.f;
; #pragma unroll
;                 for (int j = 0; j < 8; ++j) ss += f[j] * f[j];
;                 ss += shx(ss, lane, 1); ss += shx(ss, lane, 2); ss += shx(ss, lane, 4); ss += shx(ss, lane, 8);
;                 const float rs = rsqrtf(ss * (1.0f / 128.0f) + EPS);
; #pragma unroll
;                 for (int j = 0; j < 8; ++j) f[j] *= rs * (it < 4 ? gq[j] : gk[j]);
;                 u32x4 o; o.x = cvt_pk_bf16(f[0], f[1]); o.y = cvt_pk_bf16(f[2], f[3]); o.z = cvt_pk_bf16(f[4], f[5]); o.w = cvt_pk_bf16(f[6], f[7]);
;                 if (it < 4) *(LAS u32x4*)(lds + QI + (rr + 32 * it) * PA + c16 * 16) = o;
;                 else *(LAS u32x4*)(lds + KI + (rr + 32 * (it - 4)) * PA + c16 * 16) = o;
	v_rsq_f32_e32 v72, v72
	s_nop 0
	v_mul_f32_e32 v73, v67, v72
	v_mul_f32_e32 v71, v73, v71
	v_mul_f32_e32 v73, v70, v72
	v_mul_f32_e32 v73, v73, v74
	v_mul_f32_e32 v74, v69, v72
	v_mul_f32_e32 v3, v74, v3
	v_mul_f32_e32 v74, v68, v72
	v_mul_f32_e32 v2, v74, v2
	v_mul_f32_e32 v74, v66, v72
	v_mul_f32_e32 v74, v74, v61
	v_mul_f32_e32 v61, v65, v72
	v_mul_f32_e32 v75, v61, v60
	v_mul_f32_e32 v60, v64, v72
	v_mul_f32_e32 v63, v60, v63
	v_mul_f32_e32 v60, v1, v72
	v_mul_f32_e32 v72, v60, v62
	v_cvt_pk_bf16_f32 v60, v71, v73
	v_cvt_pk_bf16_f32 v61, v3, v2
	v_cvt_pk_bf16_f32 v62, v74, v75
	v_and_b32_e32 v74, 0xffff0000, v16
	v_cvt_pk_bf16_f32 v63, v63, v72
	ds_write_b128 v108, v[60:63] offset:17408
	v_lshlrev_b32_e32 v71, 16, v16
	v_mul_f32_e32 v62, v74, v74
	v_and_b32_e32 v2, 0xffff0000, v17
	v_lshlrev_b32_e32 v3, 16, v17
	v_fmac_f32_e32 v62, v71, v71
	v_pk_mul_f32 v[60:61], v[2:3], v[2:3]
	s_nop 0
	v_add_f32_e32 v61, v61, v62
	v_add_f32_e32 v72, v60, v61
	v_and_b32_e32 v60, 0xffff0000, v18
	v_lshlrev_b32_e32 v61, 16, v18
	v_pk_mul_f32 v[62:63], v[60:61], v[60:61]
	s_nop 0
	v_add_f32_e32 v63, v63, v72
	v_add_f32_e32 v75, v62, v63
	v_and_b32_e32 v62, 0xffff0000, v19
	v_lshlrev_b32_e32 v63, 16, v19
	v_pk_mul_f32 v[72:73], v[62:63], v[62:63]
	s_nop 0
	v_add_f32_e32 v73, v73, v75
	v_add_f32_e32 v72, v72, v73
	s_nop 1
	v_add_f32_dpp v72, v72, v72 quad_perm:[1,0,3,2] row_mask:0xf bank_mask:0xf
	s_nop 1
	v_add_f32_dpp v72, v72, v72 quad_perm:[2,3,0,1] row_mask:0xf bank_mask:0xf
	s_nop 1
	v_add_f32_dpp v72, v72, v72 row_half_mirror row_mask:0xf bank_mask:0xf
	s_nop 1
	v_add_f32_dpp v72, v72, v72 row_mirror row_mask:0xf bank_mask:0xf
	v_fmamk_f32 v72, v72, 0x3c000000, v185
	v_rsq_f32_e32 v72, v72
	s_nop 0
	v_mul_f32_e32 v66, v66, v72
	v_mul_f32_e32 v66, v66, v61
	v_mul_f32_e32 v61, v65, v72
	v_mul_f32_e32 v67, v67, v72
	v_mul_f32_e32 v70, v70, v72
	v_mul_f32_e32 v69, v69, v72
	v_mul_f32_e32 v68, v68, v72
	v_mul_f32_e32 v65, v61, v60
	v_mul_f32_e32 v60, v64, v72
	v_mul_f32_e32 v1, v1, v72
	v_mul_f32_e32 v67, v67, v71
	v_mul_f32_e32 v70, v70, v74
	v_mul_f32_e32 v3, v69, v3
	v_mul_f32_e32 v2, v68, v2
	v_mul_f32_e32 v63, v60, v63
	v_mul_f32_e32 v1, v1, v62
	v_cvt_pk_bf16_f32 v60, v67, v70
	v_cvt_pk_bf16_f32 v61, v3, v2
	v_cvt_pk_bf16_f32 v62, v66, v65
	v_and_b32_e32 v66, 0xffff0000, v24
	v_cvt_pk_bf16_f32 v63, v63, v1
	ds_write_b128 v108, v[60:63] offset:26112
	v_lshlrev_b32_e32 v1, 16, v24
	v_mul_f32_e32 v62, v66, v66
	v_and_b32_e32 v2, 0xffff0000, v25
	v_lshlrev_b32_e32 v3, 16, v25
	v_fmac_f32_e32 v62, v1, v1
	v_pk_mul_f32 v[60:61], v[2:3], v[2:3]
	s_nop 0
	v_add_f32_e32 v61, v61, v62
	v_add_f32_e32 v64, v60, v61
	v_and_b32_e32 v60, 0xffff0000, v26
	v_lshlrev_b32_e32 v61, 16, v26
	v_pk_mul_f32 v[62:63], v[60:61], v[60:61]
	s_nop 0
	v_add_f32_e32 v63, v63, v64
	v_add_f32_e32 v67, v62, v63
	v_and_b32_e32 v62, 0xffff0000, v27
	v_lshlrev_b32_e32 v63, 16, v27
	v_pk_mul_f32 v[64:65], v[62:63], v[62:63]
	s_nop 0
	v_add_f32_e32 v65, v65, v67
	v_add_f32_e32 v64, v64, v65
	s_nop 1
	v_add_f32_dpp v64, v64, v64 quad_perm:[1,0,3,2] row_mask:0xf bank_mask:0xf
	s_nop 1
	v_add_f32_dpp v64, v64, v64 quad_perm:[2,3,0,1] row_mask:0xf bank_mask:0xf
	s_nop 1
	v_add_f32_dpp v64, v64, v64 row_half_mirror row_mask:0xf bank_mask:0xf
	s_nop 1
	v_add_f32_dpp v64, v64, v64 row_mirror row_mask:0xf bank_mask:0xf
	v_fmamk_f32 v64, v64, 0x3c000000, v185
	v_rsq_f32_e32 v64, v64
	s_nop 0
	s_waitcnt vmcnt(0)
	v_mul_f32_e32 v65, v56, v64
	v_mul_f32_e32 v1, v65, v1
	v_mul_f32_e32 v65, v57, v64
	v_mul_f32_e32 v65, v65, v66
	v_mul_f32_e32 v66, v58, v64
	v_mul_f32_e32 v3, v66, v3
	v_mul_f32_e32 v66, v59, v64
	v_mul_f32_e32 v2, v66, v2
	v_mul_f32_e32 v66, v52, v64
	v_mul_f32_e32 v66, v66, v61
	v_mul_f32_e32 v61, v53, v64
	v_mul_f32_e32 v67, v61, v60
	v_mul_f32_e32 v60, v54, v64
	v_mul_f32_e32 v63, v60, v63
	v_mul_f32_e32 v60, v55, v64
	v_mul_f32_e32 v64, v60, v62
	v_cvt_pk_bf16_f32 v60, v1, v65
	v_cvt_pk_bf16_f32 v61, v3, v2
	v_cvt_pk_bf16_f32 v62, v66, v67
	v_and_b32_e32 v66, 0xffff0000, v20
	v_cvt_pk_bf16_f32 v63, v63, v64
	ds_write_b128 v108, v[60:63] offset:34816
	v_lshlrev_b32_e32 v1, 16, v20
	v_mul_f32_e32 v62, v66, v66
	v_and_b32_e32 v2, 0xffff0000, v21
	v_lshlrev_b32_e32 v3, 16, v21
	v_fmac_f32_e32 v62, v1, v1
	v_pk_mul_f32 v[60:61], v[2:3], v[2:3]
	s_nop 0
	v_add_f32_e32 v61, v61, v62
	v_add_f32_e32 v64, v60, v61
	v_and_b32_e32 v60, 0xffff0000, v22
	v_lshlrev_b32_e32 v61, 16, v22
	v_pk_mul_f32 v[62:63], v[60:61], v[60:61]
	s_nop 0
	v_add_f32_e32 v63, v63, v64
	v_add_f32_e32 v67, v62, v63
	v_and_b32_e32 v62, 0xffff0000, v23
	v_lshlrev_b32_e32 v63, 16, v23
	v_pk_mul_f32 v[64:65], v[62:63], v[62:63]
	s_nop 0
	v_add_f32_e32 v65, v65, v67
	v_add_f32_e32 v64, v64, v65
	s_nop 1
	v_add_f32_dpp v64, v64, v64 quad_perm:[1,0,3,2] row_mask:0xf bank_mask:0xf
	s_nop 1
	v_add_f32_dpp v64, v64, v64 quad_perm:[2,3,0,1] row_mask:0xf bank_mask:0xf
	s_nop 1
	v_add_f32_dpp v64, v64, v64 row_half_mirror row_mask:0xf bank_mask:0xf
	s_nop 1
	v_add_f32_dpp v64, v64, v64 row_mirror row_mask:0xf bank_mask:0xf
	v_fmamk_f32 v64, v64, 0x3c000000, v185
	v_rsq_f32_e32 v64, v64
	s_nop 0
	v_mul_f32_e32 v65, v56, v64
	v_mul_f32_e32 v1, v65, v1
	v_mul_f32_e32 v65, v57, v64
	v_mul_f32_e32 v65, v65, v66
	v_mul_f32_e32 v66, v58, v64
	v_mul_f32_e32 v3, v66, v3
	v_mul_f32_e32 v66, v59, v64
	v_mul_f32_e32 v2, v66, v2
	v_mul_f32_e32 v66, v52, v64
	v_mul_f32_e32 v66, v66, v61
	v_mul_f32_e32 v61, v53, v64
	v_mul_f32_e32 v67, v61, v60
	v_mul_f32_e32 v60, v54, v64
	v_mul_f32_e32 v63, v60, v63
	v_mul_f32_e32 v60, v55, v64
	v_mul_f32_e32 v64, v60, v62
	v_cvt_pk_bf16_f32 v60, v1, v65
	v_cvt_pk_bf16_f32 v61, v3, v2
	v_cvt_pk_bf16_f32 v62, v66, v67
; #define LAS __attribute__((address_space(3)))
; __device__ __forceinline__ float shx(float v, int lane, int mask) { return __int_as_float(__builtin_amdgcn_ds_bpermute((lane ^ mask) << 2, __float_as_int(v))); }
; __device__ __forceinline__ unsigned cvt_pk_bf16(float lo, float hi) { unsigned r; asm volatile("v_cvt_pk_bf16_f32 %0, %1, %2" : "=v"(r) : "v"(lo), "v"(hi)); return r; }
; __device__ __forceinline__ float bflo(unsigned u) { return __uint_as_float(u << 16); }
; __device__ __forceinline__ float bfhi(unsigned u) { return __uint_as_float(u & 0xffff0000u); }
; __device__ __forceinline__ void attn_stream(const int wv, LAS unsigned char* lds, unsigned ldsb, const float* __restrict__ qng, const float* __restrict__ kng, const bf16_t* __restrict__ qkvr, bf16_t* __restrict__ og, float* __restrict__ lse, ...
;     ...
;             for (int j = 0; j < 8; ++j) { gq[j] = qng[hh * 128 + c8 + j] * 0.08838834764831845f; gk[j] = kng[hh * 128 + c8 + j]; }
; #pragma unroll
;             for (int it = 0; it < 12; ++it) {
;                 const u32x4 v = it < 4 ? qr[it] : kr[it - 4];
;                 float f[8] = {bflo(v.x), bfhi(v.x), bflo(v.y), bfhi(v.y), bflo(v.z), bfhi(v.z), bflo(v.w), bfhi(v.w)};
;                 float ss = 0.f;
; #pragma unroll
;                 for (int j = 0; j < 8; ++j) ss += f[j] * f[j];
;                 ss += shx(ss, lane, 1); ss += shx(ss, lane, 2); ss += shx(ss, lane, 4); ss += shx(ss, lane, 8);
;                 const float rs = rsqrtf(ss * (1.0f / 128.0f) + EPS);
; #pragma unroll
;                 for (int j = 0; j < 8; ++j) f[j] *= rs * (it < 4 ? gq[j] : gk[j]);
;                 u32x4 o; o.x = cvt_pk_bf16(f[0], f[1]); o.y = cvt_pk_bf16(f[2], f[3]); o.z = cvt_pk_bf16(f[4], f[5]); o.w = cvt_pk_bf16(f[6], f[7]);
;                 if (it < 4) *(LAS u32x4*)(lds + QI + (rr + 32 * it) * PA + c16 * 16) = o;
;                 else *(LAS u32x4*)(lds + KI + (rr + 32 * (it - 4)) * PA + c16 * 16) = o;
	v_and_b32_e32 v66, 0xffff0000, v28
	v_cvt_pk_bf16_f32 v63, v63, v64
	ds_write_b128 v108, v[60:63] offset:43520
	v_lshlrev_b32_e32 v1, 16, v28
	v_mul_f32_e32 v62, v66, v66
	v_and_b32_e32 v2, 0xffff0000, v29
	v_lshlrev_b32_e32 v3, 16, v29
	v_fmac_f32_e32 v62, v1, v1
	v_pk_mul_f32 v[60:61], v[2:3], v[2:3]
	s_nop 0
	v_add_f32_e32 v61, v61, v62
	v_add_f32_e32 v64, v60, v61
	v_and_b32_e32 v60, 0xffff0000, v30
	v_lshlrev_b32_e32 v61, 16, v30
	v_pk_mul_f32 v[62:63], v[60:61], v[60:61]
	s_nop 0
	v_add_f32_e32 v63, v63, v64
	v_add_f32_e32 v67, v62, v63
	v_and_b32_e32 v62, 0xffff0000, v31
	v_lshlrev_b32_e32 v63, 16, v31
	v_pk_mul_f32 v[64:65], v[62:63], v[62:63]
	s_nop 0
	v_add_f32_e32 v65, v65, v67
	v_add_f32_e32 v64, v64, v65
	s_nop 1
	v_add_f32_dpp v64, v64, v64 quad_perm:[1,0,3,2] row_mask:0xf bank_mask:0xf
	s_nop 1
	v_add_f32_dpp v64, v64, v64 quad_perm:[2,3,0,1] row_mask:0xf bank_mask:0xf
	s_nop 1
	v_add_f32_dpp v64, v64, v64 row_half_mirror row_mask:0xf bank_mask:0xf
	s_nop 1
	v_add_f32_dpp v64, v64, v64 row_mirror row_mask:0xf bank_mask:0xf
	v_fmamk_f32 v64, v64, 0x3c000000, v185
	v_rsq_f32_e32 v64, v64
	s_nop 0
	v_mul_f32_e32 v65, v56, v64
	v_mul_f32_e32 v1, v65, v1
	v_mul_f32_e32 v65, v57, v64
	v_mul_f32_e32 v65, v65, v66
	v_mul_f32_e32 v66, v58, v64
	v_mul_f32_e32 v3, v66, v3
	v_mul_f32_e32 v66, v59, v64
	v_mul_f32_e32 v2, v66, v2
	v_mul_f32_e32 v66, v52, v64
	v_mul_f32_e32 v66, v66, v61
	v_mul_f32_e32 v61, v53, v64
	v_mul_f32_e32 v67, v61, v60
	v_mul_f32_e32 v60, v54, v64
	v_mul_f32_e32 v63, v60, v63
	v_mul_f32_e32 v60, v55, v64
	v_mul_f32_e32 v64, v60, v62
	v_cvt_pk_bf16_f32 v60, v1, v65
	v_cvt_pk_bf16_f32 v61, v3, v2
	v_cvt_pk_bf16_f32 v62, v66, v67
	v_and_b32_e32 v66, 0xffff0000, v32
	v_cvt_pk_bf16_f32 v63, v63, v64
	ds_write_b128 v108, v[60:63] offset:52224
	v_lshlrev_b32_e32 v1, 16, v32
	v_mul_f32_e32 v62, v66, v66
	v_and_b32_e32 v2, 0xffff0000, v33
	v_lshlrev_b32_e32 v3, 16, v33
	v_fmac_f32_e32 v62, v1, v1
	v_pk_mul_f32 v[60:61], v[2:3], v[2:3]
	s_nop 0
	v_add_f32_e32 v61, v61, v62
	v_add_f32_e32 v64, v60, v61
	v_and_b32_e32 v60, 0xffff0000, v34
	v_lshlrev_b32_e32 v61, 16, v34
	v_pk_mul_f32 v[62:63], v[60:61], v[60:61]
	s_nop 0
	v_add_f32_e32 v63, v63, v64
	v_add_f32_e32 v67, v62, v63
	v_and_b32_e32 v62, 0xffff0000, v35
	v_lshlrev_b32_e32 v63, 16, v35
	v_pk_mul_f32 v[64:65], v[62:63], v[62:63]
	s_nop 0
	v_add_f32_e32 v65, v65, v67
	v_add_f32_e32 v64, v64, v65
	s_nop 1
	v_add_f32_dpp v64, v64, v64 quad_perm:[1,0,3,2] row_mask:0xf bank_mask:0xf
	s_nop 1
	v_add_f32_dpp v64, v64, v64 quad_perm:[2,3,0,1] row_mask:0xf bank_mask:0xf
	s_nop 1
	v_add_f32_dpp v64, v64, v64 row_half_mirror row_mask:0xf bank_mask:0xf
	s_nop 1
	v_add_f32_dpp v64, v64, v64 row_mirror row_mask:0xf bank_mask:0xf
	v_fmamk_f32 v64, v64, 0x3c000000, v185
	v_rsq_f32_e32 v64, v64
	s_nop 0
	v_mul_f32_e32 v65, v56, v64
	v_mul_f32_e32 v1, v65, v1
	v_mul_f32_e32 v65, v57, v64
	v_mul_f32_e32 v65, v65, v66
	v_mul_f32_e32 v66, v58, v64
	v_mul_f32_e32 v3, v66, v3
	v_mul_f32_e32 v66, v59, v64
	v_mul_f32_e32 v2, v66, v2
	v_mul_f32_e32 v66, v52, v64
	v_mul_f32_e32 v66, v66, v61
	v_mul_f32_e32 v61, v53, v64
	v_mul_f32_e32 v67, v61, v60
	v_mul_f32_e32 v60, v54, v64
	v_mul_f32_e32 v63, v60, v63
	v_mul_f32_e32 v60, v55, v64
	v_mul_f32_e32 v64, v60, v62
	v_cvt_pk_bf16_f32 v60, v1, v65
	v_cvt_pk_bf16_f32 v61, v3, v2
	v_cvt_pk_bf16_f32 v62, v66, v67
	v_and_b32_e32 v66, 0xffff0000, v36
	v_cvt_pk_bf16_f32 v63, v63, v64
	ds_write_b128 v108, v[60:63] offset:60928
	v_lshlrev_b32_e32 v1, 16, v36
	v_mul_f32_e32 v62, v66, v66
	v_and_b32_e32 v2, 0xffff0000, v37
	v_lshlrev_b32_e32 v3, 16, v37
	v_fmac_f32_e32 v62, v1, v1
	v_pk_mul_f32 v[60:61], v[2:3], v[2:3]
	s_nop 0
	v_add_f32_e32 v61, v61, v62
	v_add_f32_e32 v64, v60, v61
	v_and_b32_e32 v60, 0xffff0000, v38
	v_lshlrev_b32_e32 v61, 16, v38
	v_pk_mul_f32 v[62:63], v[60:61], v[60:61]
	s_nop 0
	v_add_f32_e32 v63, v63, v64
	v_add_f32_e32 v67, v62, v63
	v_and_b32_e32 v62, 0xffff0000, v39
	v_lshlrev_b32_e32 v63, 16, v39
	v_pk_mul_f32 v[64:65], v[62:63], v[62:63]
	s_nop 0
	v_add_f32_e32 v65, v65, v67
	v_add_f32_e32 v64, v64, v65
	s_nop 1
	v_add_f32_dpp v64, v64, v64 quad_perm:[1,0,3,2] row_mask:0xf bank_mask:0xf
	s_nop 1
	v_add_f32_dpp v64, v64, v64 quad_perm:[2,3,0,1] row_mask:0xf bank_mask:0xf
	s_nop 1
	v_add_f32_dpp v64, v64, v64 row_half_mirror row_mask:0xf bank_mask:0xf
	s_nop 1
	v_add_f32_dpp v64, v64, v64 row_mirror row_mask:0xf bank_mask:0xf
	v_fmamk_f32 v64, v64, 0x3c000000, v185
	v_rsq_f32_e32 v64, v64
	s_nop 0
	v_mul_f32_e32 v65, v56, v64
	v_mul_f32_e32 v1, v65, v1
	v_mul_f32_e32 v65, v57, v64
	v_mul_f32_e32 v65, v65, v66
	v_mul_f32_e32 v66, v58, v64
	v_mul_f32_e32 v3, v66, v3
	v_mul_f32_e32 v66, v59, v64
	v_mul_f32_e32 v2, v66, v2
	v_mul_f32_e32 v66, v52, v64
	v_mul_f32_e32 v66, v66, v61
	v_mul_f32_e32 v61, v53, v64
	v_mul_f32_e32 v67, v61, v60
	v_mul_f32_e32 v60, v54, v64
	v_mul_f32_e32 v63, v60, v63
	v_mul_f32_e32 v60, v55, v64
	v_mul_f32_e32 v64, v60, v62
	v_cvt_pk_bf16_f32 v60, v1, v65
	v_cvt_pk_bf16_f32 v61, v3, v2
	v_cvt_pk_bf16_f32 v62, v66, v67
	v_and_b32_e32 v66, 0xffff0000, v40
	v_cvt_pk_bf16_f32 v63, v63, v64
	ds_write_b128 v109, v[60:63] offset:34816
	v_lshlrev_b32_e32 v1, 16, v40
	v_mul_f32_e32 v62, v66, v66
	v_and_b32_e32 v2, 0xffff0000, v41
	v_lshlrev_b32_e32 v3, 16, v41
	v_fmac_f32_e32 v62, v1, v1
	v_pk_mul_f32 v[60:61], v[2:3], v[2:3]
	s_nop 0
	v_add_f32_e32 v61, v61, v62
	v_add_f32_e32 v64, v60, v61
	v_and_b32_e32 v60, 0xffff0000, v42
; #define LAS __attribute__((address_space(3)))
; __device__ __forceinline__ float shx(float v, int lane, int mask) { return __int_as_float(__builtin_amdgcn_ds_bpermute((lane ^ mask) << 2, __float_as_int(v))); }
; __device__ __forceinline__ unsigned cvt_pk_bf16(float lo, float hi) { unsigned r; asm volatile("v_cvt_pk_bf16_f32 %0, %1, %2" : "=v"(r) : "v"(lo), "v"(hi)); return r; }
; __device__ __forceinline__ float bflo(unsigned u) { return __uint_as_float(u << 16); }
; __device__ __forceinline__ float bfhi(unsigned u) { return __uint_as_float(u & 0xffff0000u); }
; __device__ __forceinline__ void attn_stream(const int wv, LAS unsigned char* lds, unsigned ldsb, const float* __restrict__ qng, const float* __restrict__ kng, const bf16_t* __restrict__ qkvr, bf16_t* __restrict__ og, float* __restrict__ lse, ...
;     ...
;             for (int j = 0; j < 8; ++j) { gq[j] = qng[hh * 128 + c8 + j] * 0.08838834764831845f; gk[j] = kng[hh * 128 + c8 + j]; }
; #pragma unroll
;             for (int it = 0; it < 12; ++it) {
;                 const u32x4 v = it < 4 ? qr[it] : kr[it - 4];
;                 float f[8] = {bflo(v.x), bfhi(v.x), bflo(v.y), bfhi(v.y), bflo(v.z), bfhi(v.z), bflo(v.w), bfhi(v.w)};
;                 float ss = 0.f;
; #pragma unroll
;                 for (int j = 0; j < 8; ++j) ss += f[j] * f[j];
;                 ss += shx(ss, lane, 1); ss += shx(ss, lane, 2); ss += shx(ss, lane, 4); ss += shx(ss, lane, 8);
;                 const float rs = rsqrtf(ss * (1.0f / 128.0f) + EPS);
; #pragma unroll
;                 for (int j = 0; j < 8; ++j) f[j] *= rs * (it < 4 ? gq[j] : gk[j]);
;                 u32x4 o; o.x = cvt_pk_bf16(f[0], f[1]); o.y = cvt_pk_bf16(f[2], f[3]); o.z = cvt_pk_bf16(f[4], f[5]); o.w = cvt_pk_bf16(f[6], f[7]);
;                 if (it < 4) *(LAS u32x4*)(lds + QI + (rr + 32 * it) * PA + c16 * 16) = o;
;                 else *(LAS u32x4*)(lds + KI + (rr + 32 * (it - 4)) * PA + c16 * 16) = o;
;             }
;         }
;         __syncthreads();
; #pragma unroll
;         for (int it = 0; it < 8; ++it) { const int l = n * 128 - 128 + rr + 32 * it; vr[it] = (u32x4){0u, 0u, 0u, 0u};
;             if (l >= 0) vr[it] = *(const u32x4*)(qkvr + (size_t)(l * dil + r) * QKVR_LD + C_AV + hh * 128 + c16 * 8); }
	v_lshlrev_b32_e32 v61, 16, v42
	v_pk_mul_f32 v[62:63], v[60:61], v[60:61]
	s_nop 0
	v_add_f32_e32 v63, v63, v64
	v_add_f32_e32 v67, v62, v63
	v_and_b32_e32 v62, 0xffff0000, v43
	v_lshlrev_b32_e32 v63, 16, v43
	v_pk_mul_f32 v[64:65], v[62:63], v[62:63]
	s_nop 0
	v_add_f32_e32 v65, v65, v67
	v_add_f32_e32 v64, v64, v65
	s_nop 1
	v_add_f32_dpp v64, v64, v64 quad_perm:[1,0,3,2] row_mask:0xf bank_mask:0xf
	s_nop 1
	v_add_f32_dpp v64, v64, v64 quad_perm:[2,3,0,1] row_mask:0xf bank_mask:0xf
	s_nop 1
	v_add_f32_dpp v64, v64, v64 row_half_mirror row_mask:0xf bank_mask:0xf
	s_nop 1
	v_add_f32_dpp v64, v64, v64 row_mirror row_mask:0xf bank_mask:0xf
	v_fmamk_f32 v64, v64, 0x3c000000, v185
	v_rsq_f32_e32 v64, v64
	s_nop 0
	v_mul_f32_e32 v65, v56, v64
	v_mul_f32_e32 v1, v65, v1
	v_mul_f32_e32 v65, v57, v64
	v_mul_f32_e32 v65, v65, v66
	v_mul_f32_e32 v66, v58, v64
	v_mul_f32_e32 v3, v66, v3
	v_mul_f32_e32 v66, v59, v64
	v_mul_f32_e32 v2, v66, v2
	v_mul_f32_e32 v66, v52, v64
	v_mul_f32_e32 v66, v66, v61
	v_mul_f32_e32 v61, v53, v64
	v_mul_f32_e32 v67, v61, v60
	v_mul_f32_e32 v60, v54, v64
	v_mul_f32_e32 v63, v60, v63
	v_mul_f32_e32 v60, v55, v64
	v_mul_f32_e32 v64, v60, v62
	v_cvt_pk_bf16_f32 v60, v1, v65
	v_cvt_pk_bf16_f32 v61, v3, v2
	v_cvt_pk_bf16_f32 v62, v66, v67
	v_and_b32_e32 v66, 0xffff0000, v44
	v_cvt_pk_bf16_f32 v63, v63, v64
	ds_write_b128 v109, v[60:63] offset:43520
	v_lshlrev_b32_e32 v1, 16, v44
	v_mul_f32_e32 v62, v66, v66
	v_and_b32_e32 v2, 0xffff0000, v45
	v_lshlrev_b32_e32 v3, 16, v45
	v_fmac_f32_e32 v62, v1, v1
	v_pk_mul_f32 v[60:61], v[2:3], v[2:3]
	s_nop 0
	v_add_f32_e32 v61, v61, v62
	v_add_f32_e32 v64, v60, v61
	v_and_b32_e32 v60, 0xffff0000, v46
	v_lshlrev_b32_e32 v61, 16, v46
	v_pk_mul_f32 v[62:63], v[60:61], v[60:61]
	s_nop 0
	v_add_f32_e32 v63, v63, v64
	v_add_f32_e32 v67, v62, v63
	v_and_b32_e32 v62, 0xffff0000, v47
	v_lshlrev_b32_e32 v63, 16, v47
	v_pk_mul_f32 v[64:65], v[62:63], v[62:63]
	s_nop 0
	v_add_f32_e32 v65, v65, v67
	v_add_f32_e32 v64, v64, v65
	s_nop 1
	v_add_f32_dpp v64, v64, v64 quad_perm:[1,0,3,2] row_mask:0xf bank_mask:0xf
	s_nop 1
	v_add_f32_dpp v64, v64, v64 quad_perm:[2,3,0,1] row_mask:0xf bank_mask:0xf
	s_nop 1
	v_add_f32_dpp v64, v64, v64 row_half_mirror row_mask:0xf bank_mask:0xf
	s_nop 1
	v_add_f32_dpp v64, v64, v64 row_mirror row_mask:0xf bank_mask:0xf
	v_fmamk_f32 v64, v64, 0x3c000000, v185
	v_rsq_f32_e32 v64, v64
	s_nop 0
	v_mul_f32_e32 v65, v56, v64
	v_mul_f32_e32 v1, v65, v1
	v_mul_f32_e32 v65, v57, v64
	v_mul_f32_e32 v65, v65, v66
	v_mul_f32_e32 v66, v58, v64
	v_mul_f32_e32 v3, v66, v3
	v_mul_f32_e32 v66, v59, v64
	v_mul_f32_e32 v2, v66, v2
	v_mul_f32_e32 v66, v52, v64
	v_mul_f32_e32 v66, v66, v61
	v_mul_f32_e32 v61, v53, v64
	v_mul_f32_e32 v67, v61, v60
	v_mul_f32_e32 v60, v54, v64
	v_mul_f32_e32 v63, v60, v63
	v_mul_f32_e32 v60, v55, v64
	v_mul_f32_e32 v64, v60, v62
	v_cvt_pk_bf16_f32 v60, v1, v65
	v_cvt_pk_bf16_f32 v61, v3, v2
	v_cvt_pk_bf16_f32 v62, v66, v67
	v_and_b32_e32 v66, 0xffff0000, v48
	v_cvt_pk_bf16_f32 v63, v63, v64
	ds_write_b128 v109, v[60:63] offset:52224
	v_lshlrev_b32_e32 v1, 16, v48
	v_mul_f32_e32 v62, v66, v66
	v_and_b32_e32 v2, 0xffff0000, v49
	v_lshlrev_b32_e32 v3, 16, v49
	v_fmac_f32_e32 v62, v1, v1
	v_pk_mul_f32 v[60:61], v[2:3], v[2:3]
	s_nop 0
	v_add_f32_e32 v61, v61, v62
	v_add_f32_e32 v64, v60, v61
	v_and_b32_e32 v60, 0xffff0000, v50
	v_lshlrev_b32_e32 v61, 16, v50
	v_pk_mul_f32 v[62:63], v[60:61], v[60:61]
	s_nop 0
	v_add_f32_e32 v63, v63, v64
	v_add_f32_e32 v67, v62, v63
	v_and_b32_e32 v62, 0xffff0000, v51
	v_lshlrev_b32_e32 v63, 16, v51
	v_pk_mul_f32 v[64:65], v[62:63], v[62:63]
	s_nop 0
	v_add_f32_e32 v65, v65, v67
	v_add_f32_e32 v64, v64, v65
	s_nop 1
	v_add_f32_dpp v64, v64, v64 quad_perm:[1,0,3,2] row_mask:0xf bank_mask:0xf
	s_nop 1
	v_add_f32_dpp v64, v64, v64 quad_perm:[2,3,0,1] row_mask:0xf bank_mask:0xf
	s_nop 1
	v_add_f32_dpp v64, v64, v64 row_half_mirror row_mask:0xf bank_mask:0xf
	s_nop 1
	v_add_f32_dpp v64, v64, v64 row_mirror row_mask:0xf bank_mask:0xf
	v_fmamk_f32 v64, v64, 0x3c000000, v185
	v_rsq_f32_e32 v64, v64
	s_nop 0
	v_mul_f32_e32 v56, v56, v64
	v_mul_f32_e32 v1, v56, v1
	v_mul_f32_e32 v56, v57, v64
	v_mul_f32_e32 v57, v58, v64
	v_mul_f32_e32 v3, v57, v3
	v_mul_f32_e32 v57, v59, v64
	v_mul_f32_e32 v52, v52, v64
	v_mul_f32_e32 v2, v57, v2
	v_mul_f32_e32 v57, v52, v61
	v_mul_f32_e32 v52, v53, v64
	v_mul_f32_e32 v58, v52, v60
	v_mul_f32_e32 v52, v54, v64
	v_mul_f32_e32 v59, v52, v63
	v_mul_f32_e32 v52, v55, v64
	v_mul_f32_e32 v56, v56, v66
	v_mul_f32_e32 v55, v52, v62
	v_cvt_pk_bf16_f32 v52, v1, v56
	v_add_u32_e32 v1, 0xffffff80, v130
	v_add_u32_e32 v1, s20, v1
	v_cvt_pk_bf16_f32 v53, v3, v2
	v_cvt_pk_bf16_f32 v54, v57, v58
	v_cvt_pk_bf16_f32 v55, v59, v55
	ds_write_b128 v109, v[52:55] offset:60928
	v_cmp_lt_i32_e32 vcc, -1, v1
	v_mov_b32_e32 v52, 0
	v_lshlrev_b32_e32 v2, 1, v104
	v_mov_b32_e32 v56, 0
	v_mov_b32_e32 v57, 0
	v_mov_b32_e32 v58, 0
	v_mov_b32_e32 v59, 0
	s_waitcnt lgkmcnt(0)
	s_barrier
	s_and_saveexec_b64 s[12:13], vcc
	s_cbranch_execz .LBB0_331
	v_lshlrev_b32_e32 v3, s18, v1
	v_add_u32_e32 v3, s19, v3
	v_mov_b64_e32 v[54:55], s[90:91]
	v_mad_u64_u32 v[54:55], vcc, v3, s33, v[54:55]
	v_lshl_add_u64 v[54:55], s[92:93], 1, v[54:55]
	v_mov_b32_e32 v3, v0
	v_lshl_add_u64 v[54:55], v[54:55], 0, v[2:3]
	v_add_co_u32_e32 v54, vcc, 0x1000, v54
	s_nop 1
	v_addc_co_u32_e32 v55, vcc, 0, v55, vcc
	global_load_dwordx4 v[56:59], v[54:55], off offset:2048
